# D-attention loop: first softmax block interleaved into the second QK MFMA group (hides 3 MFMAs per wave per tile)
# baseline (speedup 1.0000x reference)
; #define LAS __attribute__((address_space(3)))
; DI unsigned pk2(float lo, float hi) { f32x2 v = {lo, hi}; bf16x2_t b = __builtin_convertvector(v, bf16x2_t); return __builtin_bit_cast(unsigned, b); }
; DI float fast_exp2(float x) { return __builtin_amdgcn_exp2f(x); }
; DI void attn_unit_d32(const Ctx& C, const bf16_t* __restrict__ Z, bf16_t* __restrict__ Y, int b, int qsel, int hsel, bool ctxq, float lam, float post_scale, const float* subln, const float mref) {
;     ...
;         f32x16 st[2];
; #pragma unroll
;         for (int kb = 0; kb < 2; ++kb) {
; #pragma unroll
;             for (int r = 0; r < 16; ++r) st[kb][r] = negm;
; #pragma unroll
;             for (int ks = 0; ks < 4; ++ks) { const bf16x8 a = *(const LAS bf16x8*)(Ks + (32 * kb + l31) * KST + 16 * ks + 8 * hh);
;                 st[kb] = __builtin_amdgcn_mfma_f32_32x32x16_bf16(a, qf[ks], st[kb], 0, 0, 0); } }
;         bf16x8 pf[2][2]; float ps = 0.f;
; #pragma unroll
;         for (int kb = 0; kb < 2; ++kb) {
; #pragma unroll
;             for (int r = 0; r < 16; ++r) { const float p = fast_exp2(st[kb][r]); st[kb][r] = p; ps += p; }
; #pragma unroll
;             for (int s = 0; s < 2; ++s) { u32x4 pw; pw.x = pk2(st[kb][8 * s], st[kb][8 * s + 1]); pw.y = pk2(st[kb][8 * s + 2], st[kb][8 * s + 3]); pw.z = pk2(st[kb][8 * s + 4], st[kb][8 * s + 5]); pw.w = pk2(st[kb][8 * s + 6], st[kb][8 * s + 7]);
;                 pf[kb][s] = __builtin_bit_cast(bf16x8, pw); } }
.LBB0_399:
.LBB0_407:
	s_add_i32 s0, s23, 1
	s_bitcmp1_b32 s23, 0
	s_cselect_b32 s1, 0x9000, 0
	s_lshl_b32 s24, s18, 1
	s_add_i32 s24, s1, s24
	v_add3_u32 v194, s24, v183, v184
	ds_read_b128 v[84:87], v194
	ds_read_b128 v[88:91], v194 offset:32
	ds_read_b128 v[92:95], v194 offset:64
	ds_read_b128 v[96:99], v194 offset:96
	ds_read_b128 v[214:217], v194 offset:8704
	ds_read_b128 v[218:221], v194 offset:8736
	ds_read_b128 v[222:225], v194 offset:8768
	ds_read_b128 v[240:243], v194 offset:8800
	v_add3_u32 v195, s1, v183, v185
	ds_read_b128 v[244:247], v195 offset:17408
	ds_read_b128 v[210:213], v195 offset:17440
	s_waitcnt lgkmcnt(9)
	v_mfma_f32_32x32x16_bf16 v[100:115], v[84:87], v[116:119], v[4:19]
	s_waitcnt lgkmcnt(8)
	v_mfma_f32_32x32x16_bf16 v[100:115], v[88:91], v[120:123], v[100:115]
	s_waitcnt lgkmcnt(7)
	v_mfma_f32_32x32x16_bf16 v[100:115], v[92:95], v[124:127], v[100:115]
	s_waitcnt lgkmcnt(6)
	v_mfma_f32_32x32x16_bf16 v[100:115], v[96:99], v[128:131], v[100:115]
	s_waitcnt lgkmcnt(5)
	v_mfma_f32_32x32x16_bf16 v[84:99], v[214:217], v[116:119], v[4:19]
	ds_read_b128 v[214:217], v195 offset:22016
	s_nop 8
	v_exp_f32_e32 v100, v100
	v_exp_f32_e32 v101, v101
	v_exp_f32_e32 v102, v102
	v_add_f32_e32 v209, v101, v100
	v_exp_f32_e32 v103, v103
	v_add_f32_e32 v209, v102, v209
	v_exp_f32_e32 v104, v104
	v_add_f32_e32 v209, v103, v209
	v_exp_f32_e32 v105, v105
	v_add_f32_e32 v209, v104, v209
	s_waitcnt lgkmcnt(5)
	v_mfma_f32_32x32x16_bf16 v[84:99], v[218:221], v[120:123], v[84:99]
	ds_read_b128 v[218:221], v195 offset:22048
	v_exp_f32_e32 v106, v106
	v_add_f32_e32 v209, v105, v209
	v_exp_f32_e32 v107, v107
	v_add_f32_e32 v209, v106, v209
	v_exp_f32_e32 v108, v108
	v_add_f32_e32 v209, v107, v209
	v_exp_f32_e32 v109, v109
	v_add_f32_e32 v209, v108, v209
	v_exp_f32_e32 v110, v110
	v_add_f32_e32 v209, v109, v209
	s_waitcnt lgkmcnt(5)
	v_mfma_f32_32x32x16_bf16 v[84:99], v[222:225], v[124:127], v[84:99]
	ds_read_b128 v[222:225], v195 offset:26624
	v_exp_f32_e32 v111, v111
	v_add_f32_e32 v209, v110, v209
	v_exp_f32_e32 v112, v112
	v_add_f32_e32 v209, v111, v209
	v_exp_f32_e32 v113, v113
	v_add_f32_e32 v209, v112, v209
	v_exp_f32_e32 v114, v114
	v_add_f32_e32 v209, v113, v209
	v_exp_f32_e32 v115, v115
	v_add_f32_e32 v209, v114, v209
	s_waitcnt lgkmcnt(5)
	v_mfma_f32_32x32x16_bf16 v[84:99], v[240:243], v[128:131], v[84:99]
	ds_read_b128 v[240:243], v195 offset:26656
	v_cvt_pk_bf16_f32 v100, v100, v101
	v_add_f32_e32 v209, v115, v209
	v_cvt_pk_bf16_f32 v101, v102, v103
	v_cvt_pk_bf16_f32 v102, v104, v105
	v_cvt_pk_bf16_f32 v103, v106, v107
	v_cvt_pk_bf16_f32 v104, v108, v109
	v_cvt_pk_bf16_f32 v105, v110, v111
	v_cvt_pk_bf16_f32 v106, v112, v113
	v_cvt_pk_bf16_f32 v107, v114, v115
	ds_read_b128 v[108:111], v195 offset:31232
	ds_read_b128 v[112:115], v195 offset:31264
	s_waitcnt lgkmcnt(7)
	v_mfma_f32_32x32x16_bf16 v[68:83], v[244:247], v[100:103], v[68:83]
	ds_read_b128 v[244:247], v195 offset:17472
	v_exp_f32_e32 v84, v84
	v_exp_f32_e32 v85, v85
	v_add_f32_e32 v209, v84, v209
	v_exp_f32_e32 v86, v86
	v_add_f32_e32 v209, v85, v209
	s_waitcnt lgkmcnt(7)
	v_mfma_f32_32x32x16_bf16 v[68:83], v[210:213], v[104:107], v[68:83]
	ds_read_b128 v[210:213], v195 offset:17504
	v_exp_f32_e32 v87, v87
	v_add_f32_e32 v209, v86, v209
	v_exp_f32_e32 v88, v88
	v_add_f32_e32 v209, v87, v209
	v_exp_f32_e32 v89, v89
	s_waitcnt lgkmcnt(7)
	v_mfma_f32_32x32x16_bf16 v[52:67], v[214:217], v[100:103], v[52:67]
	ds_read_b128 v[214:217], v195 offset:22080
	v_add_f32_e32 v209, v88, v209
	v_exp_f32_e32 v90, v90
	v_add_f32_e32 v209, v89, v209
	v_exp_f32_e32 v91, v91
	v_add_f32_e32 v209, v90, v209
	s_waitcnt lgkmcnt(7)
	v_mfma_f32_32x32x16_bf16 v[52:67], v[218:221], v[104:107], v[52:67]
	ds_read_b128 v[218:221], v195 offset:22112
	v_exp_f32_e32 v92, v92
	v_add_f32_e32 v209, v91, v209
	v_exp_f32_e32 v93, v93
	v_add_f32_e32 v209, v92, v209
	v_exp_f32_e32 v94, v94
	s_waitcnt lgkmcnt(7)
	v_mfma_f32_32x32x16_bf16 v[36:51], v[222:225], v[100:103], v[36:51]
	ds_read_b128 v[222:225], v195 offset:26688
	v_add_f32_e32 v209, v93, v209
	v_exp_f32_e32 v95, v95
	v_add_f32_e32 v209, v94, v209
	v_exp_f32_e32 v96, v96
	v_add_f32_e32 v209, v95, v209
	s_waitcnt lgkmcnt(7)
	v_mfma_f32_32x32x16_bf16 v[36:51], v[240:243], v[104:107], v[36:51]
	ds_read_b128 v[240:243], v195 offset:26720
	v_exp_f32_e32 v97, v97
	v_add_f32_e32 v209, v96, v209
	v_exp_f32_e32 v98, v98
	v_add_f32_e32 v209, v97, v209
	v_exp_f32_e32 v99, v99
	s_waitcnt lgkmcnt(7)
	v_mfma_f32_32x32x16_bf16 v[20:35], v[108:111], v[100:103], v[20:35]
	ds_read_b128 v[108:111], v195 offset:31296
	v_add_f32_e32 v209, v98, v209
	v_cvt_pk_bf16_f32 v84, v84, v85
	v_add_f32_e32 v209, v99, v209
	v_cvt_pk_bf16_f32 v85, v86, v87
	v_cvt_pk_bf16_f32 v86, v88, v89
	s_waitcnt lgkmcnt(7)
	v_mfma_f32_32x32x16_bf16 v[20:35], v[112:115], v[104:107], v[20:35]
	ds_read_b128 v[112:115], v195 offset:31328
	v_cvt_pk_bf16_f32 v87, v90, v91
	v_cvt_pk_bf16_f32 v88, v92, v93
	v_cvt_pk_bf16_f32 v89, v94, v95
	v_cvt_pk_bf16_f32 v90, v96, v97
	v_cvt_pk_bf16_f32 v91, v98, v99
	s_cmp_gt_u32 s23, 34
	s_cbranch_scc1 .Ldt_plain
	s_bitcmp1_b32 s23, 0
	s_cbranch_scc0 .Ldt_even
